# speedup vs baseline: 1.0039x; 1.0039x over previous
.LBB0_490:
	v_readfirstlane_b32 s98, v218
	s_nop 3
	s_lshr_b32 s98, s98, 6
	s_cmp_ge_u32 s98, 4
	s_cbranch_scc1 .Lprio_skip
	s_setprio 1
